# P2b gate-GEMM epilogue ring deepened to 4 chunks in flight (ring moved to v174-205)
# baseline (speedup 1.0000x reference)
.LBB0_365:
	s_ashr_i32 s12, s76, 1
	v_mov_b32_e32 v129, v148
	v_mov_b32_e32 v128, v149
	s_and_b32 s52, s12, 0xffffff80
	s_cmp_lt_i32 s79, 1
	v_add_u32_e32 v155, s58, v129
	v_lshl_add_u32 v156, v128, 3, s59
	s_cbranch_scc1 .LBB0_369
	s_mov_b64 s[48:49], 0
	s_cmp_eq_u32 s79, 1
	s_mov_b64 s[50:51], 0
	s_cbranch_scc0 .LBB0_368
	v_add_u32_e32 v128, s52, v155
	v_ashrrev_i32_e32 v129, 31, v128
	v_add_u32_e32 v144, s76, v156
	v_add_u32_e32 v130, s75, v155
	s_waitcnt lgkmcnt(0)
	v_lshl_add_u64 v[128:129], v[128:129], 2, s[4:5]
	v_mov_b64_e32 v[146:147], s[14:15]
	v_ashrrev_i32_e32 v145, 31, v144
	global_load_dword v157, v[128:129], off
	v_mad_i64_i32 v[162:163], s[50:51], v130, s62, v[146:147]
	v_lshlrev_b64 v[128:129], 1, v[144:145]
	v_lshl_add_u64 v[158:159], v[162:163], 0, v[128:129]
	flat_load_dwordx4 v[158:161], v[158:159]
	v_ashrrev_i32_e32 v131, 31, v130
	v_add_u32_e32 v144, 0x80, v144
	v_lshlrev_b64 v[130:131], 12, v[130:131]
	v_ashrrev_i32_e32 v145, 31, v144
	v_lshl_add_u64 v[166:167], s[38:39], 0, v[130:131]
	v_lshlrev_b64 v[130:131], 1, v[144:145]
	v_lshl_add_u64 v[168:169], v[166:167], 0, v[128:129]
	v_lshl_add_u64 v[162:163], v[162:163], 0, v[130:131]
	global_load_dwordx4 v[182:185], v[162:163], off
	v_add_u32_e32 v208, 16, v155
	v_add_u32_e32 v210, s75, v208
	v_mad_i64_i32 v[212:213], s[50:51], v210, s62, v[146:147]
	v_lshl_add_u64 v[206:207], v[212:213], 0, v[128:129]
	global_load_dwordx4 v[190:193], v[206:207], off
	v_add_u32_e32 v216, 16, v155
	v_add_u32_e32 v214, s52, v216
	v_ashrrev_i32_e32 v215, 31, v214
	v_lshl_add_u64 v[214:215], v[214:215], 2, s[4:5]
	global_load_dword v194, v[214:215], off
	v_add_u32_e32 v208, 16, v155
	v_add_u32_e32 v210, s75, v208
	v_mad_i64_i32 v[212:213], s[50:51], v210, s62, v[146:147]
	v_lshl_add_u64 v[206:207], v[212:213], 0, v[130:131]
	global_load_dwordx4 v[198:201], v[206:207], off
	s_waitcnt vmcnt(4)
	v_add_u32_e32 v208, 32, v155
	v_add_u32_e32 v210, s75, v208
	v_mad_i64_i32 v[212:213], s[50:51], v210, s62, v[146:147]
	v_lshl_add_u64 v[206:207], v[212:213], 0, v[128:129]
	global_load_dwordx4 v[174:177], v[206:207], off
	v_add_u32_e32 v216, 32, v155
	v_add_u32_e32 v214, s52, v216
	v_ashrrev_i32_e32 v215, 31, v214
	v_lshl_add_u64 v[214:215], v[214:215], 2, s[4:5]
	global_load_dword v178, v[214:215], off
	v_add_f32_e32 v123, v123, v157
	v_add_f32_e32 v124, v124, v157
	v_add_f32_e32 v125, v125, v157
	v_add_f32_e32 v126, v126, v157
	v_add_f32_e32 v127, v127, v157
	s_waitcnt lgkmcnt(0)
	v_lshlrev_b32_e32 v173, 16, v161
	v_and_b32_e32 v161, 0xffff0000, v161
	v_add_f32_e32 v120, v120, v157
	v_add_f32_e32 v121, v121, v157
	v_add_f32_e32 v122, v122, v157
	v_lshlrev_b32_e32 v170, 16, v158
	v_and_b32_e32 v158, 0xffff0000, v158
	v_lshlrev_b32_e32 v171, 16, v159
	v_and_b32_e32 v159, 0xffff0000, v159
	v_lshlrev_b32_e32 v172, 16, v160
	v_and_b32_e32 v160, 0xffff0000, v160
	v_mul_f32_e32 v123, v123, v161
	v_mul_f32_e32 v124, v124, v170
	v_mul_f32_e32 v125, v125, v158
	v_mul_f32_e32 v126, v126, v171
	v_mul_f32_e32 v127, v127, v159
	v_mul_f32_e32 v158, v120, v172
	v_mul_f32_e32 v159, v121, v160
	v_mul_f32_e32 v160, v122, v173
	v_cvt_pk_bf16_f32 v120, v124, v125
	v_cvt_pk_bf16_f32 v121, v126, v127
	v_cvt_pk_bf16_f32 v122, v158, v159
	v_cvt_pk_bf16_f32 v123, v160, v123
	flat_store_dwordx4 v[168:169], v[120:123]
	v_add_f32_e32 v116, v116, v157
	v_add_f32_e32 v117, v117, v157
	v_add_f32_e32 v118, v118, v157
	v_add_f32_e32 v119, v119, v157
	v_add_f32_e32 v112, v112, v157
	v_add_f32_e32 v113, v113, v157
	v_add_f32_e32 v114, v114, v157
	v_add_f32_e32 v115, v115, v157
	v_add_u32_e32 v125, 16, v155
	v_add_u32_e32 v124, s75, v125
	v_lshl_add_u64 v[160:161], v[166:167], 0, v[130:131]
	v_mad_i64_i32 v[126:127], s[50:51], v124, s62, v[146:147]
	v_lshl_add_u64 v[158:159], v[126:127], 0, v[128:129]
	s_waitcnt vmcnt(6) lgkmcnt(0)
	s_nop 1
	v_mov_b32_e32 v120, v182
	v_mov_b32_e32 v121, v183
	v_mov_b32_e32 v122, v184
	v_mov_b32_e32 v123, v185
	v_add_u32_e32 v208, 32, v155
	v_add_u32_e32 v210, s75, v208
	v_mad_i64_i32 v[212:213], s[50:51], v210, s62, v[146:147]
	v_lshl_add_u64 v[206:207], v[212:213], 0, v[130:131]
	global_load_dwordx4 v[182:185], v[206:207], off
	v_lshlrev_b32_e32 v157, 16, v120
	v_and_b32_e32 v120, 0xffff0000, v120
	v_lshlrev_b32_e32 v163, 16, v122
	v_mul_f32_e32 v116, v116, v157
	v_lshlrev_b32_e32 v166, 16, v123
	v_and_b32_e32 v123, 0xffff0000, v123
	v_mul_f32_e32 v117, v117, v120
	v_mul_f32_e32 v120, v112, v163
	v_cvt_pk_bf16_f32 v112, v116, v117
	v_add_u32_e32 v116, s52, v125
	v_lshlrev_b32_e32 v162, 16, v121
	v_and_b32_e32 v121, 0xffff0000, v121
	v_and_b32_e32 v122, 0xffff0000, v122
	v_mul_f32_e32 v115, v115, v123
	v_ashrrev_i32_e32 v117, 31, v116
	v_mul_f32_e32 v118, v118, v162
	v_mul_f32_e32 v119, v119, v121
	v_mul_f32_e32 v121, v113, v122
	v_mul_f32_e32 v122, v114, v166
	v_cvt_pk_bf16_f32 v113, v118, v119
	v_cvt_pk_bf16_f32 v114, v120, v121
	v_cvt_pk_bf16_f32 v115, v122, v115
	flat_store_dwordx4 v[160:161], v[112:115]
	v_lshl_add_u64 v[116:117], v[116:117], 2, s[4:5]
	v_ashrrev_i32_e32 v125, 31, v124
	v_lshlrev_b64 v[116:117], 12, v[124:125]
	v_lshl_add_u64 v[116:117], s[38:39], 0, v[116:117]
	v_lshl_add_u64 v[118:119], v[126:127], 0, v[130:131]
	v_lshl_add_u64 v[120:121], v[116:117], 0, v[128:129]
	s_waitcnt vmcnt(6) lgkmcnt(0)
	s_nop 1
	v_mov_b32_e32 v112, v190
	v_mov_b32_e32 v113, v191
	v_mov_b32_e32 v114, v192
	v_mov_b32_e32 v115, v193
	v_mov_b32_e32 v122, v194
	v_add_u32_e32 v208, 48, v155
	v_add_u32_e32 v210, s75, v208
	v_mad_i64_i32 v[212:213], s[50:51], v210, s62, v[146:147]
	v_lshl_add_u64 v[206:207], v[212:213], 0, v[128:129]
	global_load_dwordx4 v[190:193], v[206:207], off
	v_add_u32_e32 v216, 48, v155
	v_add_u32_e32 v214, s52, v216
	v_ashrrev_i32_e32 v215, 31, v214
	v_lshl_add_u64 v[214:215], v[214:215], 2, s[4:5]
	global_load_dword v194, v[214:215], off
	v_lshlrev_b32_e32 v126, 16, v115
	v_and_b32_e32 v115, 0xffff0000, v115
	v_add_f32_e32 v107, v107, v122
	v_lshlrev_b32_e32 v123, 16, v112
	v_and_b32_e32 v112, 0xffff0000, v112
	v_lshlrev_b32_e32 v124, 16, v113
	v_and_b32_e32 v113, 0xffff0000, v113
	v_lshlrev_b32_e32 v125, 16, v114
	v_and_b32_e32 v114, 0xffff0000, v114
	v_add_f32_e32 v108, v108, v122
	v_add_f32_e32 v109, v109, v122
	v_add_f32_e32 v110, v110, v122
	v_add_f32_e32 v111, v111, v122
	v_add_f32_e32 v104, v104, v122
	v_add_f32_e32 v105, v105, v122
	v_add_f32_e32 v106, v106, v122
	v_mul_f32_e32 v107, v107, v115
	v_mul_f32_e32 v108, v108, v123
	v_mul_f32_e32 v109, v109, v112
	v_mul_f32_e32 v110, v110, v124
	v_mul_f32_e32 v111, v111, v113
	v_mul_f32_e32 v112, v104, v125
	v_mul_f32_e32 v113, v105, v114
	v_mul_f32_e32 v114, v106, v126
	v_cvt_pk_bf16_f32 v104, v108, v109
	v_cvt_pk_bf16_f32 v105, v110, v111
	v_cvt_pk_bf16_f32 v106, v112, v113
	v_cvt_pk_bf16_f32 v107, v114, v107
	flat_store_dwordx4 v[120:121], v[104:107]
	v_lshl_add_u64 v[114:115], v[116:117], 0, v[130:131]
	v_add_f32_e32 v100, v100, v122
	v_add_u32_e32 v109, 32, v155
	v_add_f32_e32 v101, v101, v122
	v_add_f32_e32 v96, v96, v122
	v_add_u32_e32 v108, s75, v109
	v_add_f32_e32 v99, v99, v122
	v_mad_i64_i32 v[110:111], s[50:51], v108, s62, v[146:147]
	v_add_f32_e32 v102, v102, v122
	v_add_f32_e32 v103, v103, v122
	v_add_f32_e32 v97, v97, v122
	v_add_f32_e32 v98, v98, v122
	v_lshl_add_u64 v[112:113], v[110:111], 0, v[128:129]
	s_waitcnt vmcnt(8) lgkmcnt(0)
	s_nop 1
	v_mov_b32_e32 v104, v198
	v_mov_b32_e32 v105, v199
	v_mov_b32_e32 v106, v200
	v_mov_b32_e32 v107, v201
	v_add_u32_e32 v208, 48, v155
	v_add_u32_e32 v210, s75, v208
	v_mad_i64_i32 v[212:213], s[50:51], v210, s62, v[146:147]
	v_lshl_add_u64 v[206:207], v[212:213], 0, v[130:131]
	global_load_dwordx4 v[198:201], v[206:207], off
	v_lshlrev_b32_e32 v116, 16, v104
	v_and_b32_e32 v104, 0xffff0000, v104
	v_lshlrev_b32_e32 v118, 16, v106
	v_mul_f32_e32 v100, v100, v116
	v_lshlrev_b32_e32 v119, 16, v107
	v_and_b32_e32 v107, 0xffff0000, v107
	v_mul_f32_e32 v101, v101, v104
	v_mul_f32_e32 v104, v96, v118
	v_cvt_pk_bf16_f32 v96, v100, v101
	v_add_u32_e32 v100, s52, v109
	v_lshlrev_b32_e32 v117, 16, v105
	v_and_b32_e32 v105, 0xffff0000, v105
	v_and_b32_e32 v106, 0xffff0000, v106
	v_mul_f32_e32 v99, v99, v107
	v_ashrrev_i32_e32 v101, 31, v100
	v_mul_f32_e32 v102, v102, v117
	v_mul_f32_e32 v103, v103, v105
	v_mul_f32_e32 v105, v97, v106
	v_mul_f32_e32 v106, v98, v119
	v_cvt_pk_bf16_f32 v97, v102, v103
	v_cvt_pk_bf16_f32 v98, v104, v105
	v_cvt_pk_bf16_f32 v99, v106, v99
	flat_store_dwordx4 v[114:115], v[96:99]
	v_lshl_add_u64 v[100:101], v[100:101], 2, s[4:5]
	v_ashrrev_i32_e32 v109, 31, v108
	v_lshlrev_b64 v[100:101], 12, v[108:109]
	v_lshl_add_u64 v[100:101], s[38:39], 0, v[100:101]
	v_lshl_add_u64 v[102:103], v[110:111], 0, v[130:131]
	v_lshl_add_u64 v[104:105], v[100:101], 0, v[128:129]
	s_waitcnt vmcnt(8) lgkmcnt(0)
	s_nop 1
	v_mov_b32_e32 v96, v174
	v_mov_b32_e32 v97, v175
	v_mov_b32_e32 v98, v176
	v_mov_b32_e32 v99, v177
	v_mov_b32_e32 v106, v178
	v_lshlrev_b32_e32 v110, 16, v99
	v_and_b32_e32 v99, 0xffff0000, v99
	v_add_f32_e32 v91, v91, v106
	v_lshlrev_b32_e32 v107, 16, v96
	v_and_b32_e32 v96, 0xffff0000, v96
	v_lshlrev_b32_e32 v108, 16, v97
	v_and_b32_e32 v97, 0xffff0000, v97
	v_lshlrev_b32_e32 v109, 16, v98
	v_and_b32_e32 v98, 0xffff0000, v98
	v_add_f32_e32 v92, v92, v106
	v_add_f32_e32 v93, v93, v106
	v_add_f32_e32 v94, v94, v106
	v_add_f32_e32 v95, v95, v106
	v_add_f32_e32 v88, v88, v106
	v_add_f32_e32 v89, v89, v106
	v_add_f32_e32 v90, v90, v106
	v_mul_f32_e32 v91, v91, v99
	v_mul_f32_e32 v92, v92, v107
	v_mul_f32_e32 v93, v93, v96
	v_mul_f32_e32 v94, v94, v108
	v_mul_f32_e32 v95, v95, v97
	v_mul_f32_e32 v96, v88, v109
	v_mul_f32_e32 v97, v89, v98
	v_mul_f32_e32 v98, v90, v110
	v_cvt_pk_bf16_f32 v88, v92, v93
	v_cvt_pk_bf16_f32 v89, v94, v95
	v_cvt_pk_bf16_f32 v90, v96, v97
	v_cvt_pk_bf16_f32 v91, v98, v91
	flat_store_dwordx4 v[104:105], v[88:91]
	v_lshl_add_u64 v[98:99], v[100:101], 0, v[130:131]
	v_add_f32_e32 v84, v84, v106
	v_add_u32_e32 v93, 48, v155
	v_add_f32_e32 v85, v85, v106
	v_add_f32_e32 v80, v80, v106
	v_add_u32_e32 v92, s75, v93
	v_add_f32_e32 v83, v83, v106
	v_mad_i64_i32 v[94:95], s[50:51], v92, s62, v[146:147]
	v_add_f32_e32 v86, v86, v106
	v_add_f32_e32 v87, v87, v106
	v_add_f32_e32 v81, v81, v106
	v_add_f32_e32 v82, v82, v106
	v_lshl_add_u64 v[96:97], v[94:95], 0, v[128:129]
	s_mov_b64 s[50:51], -1
	s_waitcnt vmcnt(7) lgkmcnt(0)
	s_nop 1
	v_mov_b32_e32 v88, v182
	v_mov_b32_e32 v89, v183
	v_mov_b32_e32 v90, v184
	v_mov_b32_e32 v91, v185
	v_lshlrev_b32_e32 v100, 16, v88
	v_and_b32_e32 v88, 0xffff0000, v88
	v_lshlrev_b32_e32 v102, 16, v90
	v_mul_f32_e32 v84, v84, v100
	v_lshlrev_b32_e32 v103, 16, v91
	v_and_b32_e32 v91, 0xffff0000, v91
	v_mul_f32_e32 v85, v85, v88
	v_mul_f32_e32 v88, v80, v102
	v_cvt_pk_bf16_f32 v80, v84, v85
	v_add_u32_e32 v84, s52, v93
	v_lshlrev_b32_e32 v101, 16, v89
	v_and_b32_e32 v89, 0xffff0000, v89
	v_and_b32_e32 v90, 0xffff0000, v90
	v_mul_f32_e32 v83, v83, v91
	v_ashrrev_i32_e32 v85, 31, v84
	v_mul_f32_e32 v86, v86, v101
	v_mul_f32_e32 v87, v87, v89
	v_mul_f32_e32 v89, v81, v90
	v_mul_f32_e32 v90, v82, v103
	v_cvt_pk_bf16_f32 v81, v86, v87
	v_cvt_pk_bf16_f32 v82, v88, v89
	v_cvt_pk_bf16_f32 v83, v90, v83
	flat_store_dwordx4 v[98:99], v[80:83]
	v_lshl_add_u64 v[84:85], v[84:85], 2, s[4:5]
	v_ashrrev_i32_e32 v93, 31, v92
	v_lshlrev_b64 v[146:147], 12, v[92:93]
	v_lshl_add_u64 v[84:85], s[38:39], 0, v[146:147]
	v_lshl_add_u64 v[84:85], v[84:85], 0, v[128:129]
	v_lshl_add_u64 v[86:87], v[94:95], 0, v[130:131]
	s_waitcnt vmcnt(5) lgkmcnt(0)
	s_nop 1
	v_mov_b32_e32 v80, v190
	v_mov_b32_e32 v81, v191
	v_mov_b32_e32 v82, v192
	v_mov_b32_e32 v83, v193
	v_mov_b32_e32 v88, v194
	v_lshlrev_b32_e32 v92, 16, v83
	v_and_b32_e32 v83, 0xffff0000, v83
	v_add_f32_e32 v75, v75, v88
	v_lshlrev_b32_e32 v89, 16, v80
	v_and_b32_e32 v80, 0xffff0000, v80
	v_lshlrev_b32_e32 v90, 16, v81
	v_and_b32_e32 v81, 0xffff0000, v81
	v_lshlrev_b32_e32 v91, 16, v82
	v_and_b32_e32 v82, 0xffff0000, v82
	v_add_f32_e32 v76, v76, v88
	v_add_f32_e32 v77, v77, v88
	v_add_f32_e32 v78, v78, v88
	v_add_f32_e32 v79, v79, v88
	v_add_f32_e32 v72, v72, v88
	v_add_f32_e32 v73, v73, v88
	v_add_f32_e32 v74, v74, v88
	v_mul_f32_e32 v75, v75, v83
	v_mul_f32_e32 v76, v76, v89
	v_mul_f32_e32 v77, v77, v80
	v_mul_f32_e32 v78, v78, v90
	v_mul_f32_e32 v79, v79, v81
	v_mul_f32_e32 v80, v72, v91
	v_mul_f32_e32 v81, v73, v82
	v_mul_f32_e32 v82, v74, v92
	v_cvt_pk_bf16_f32 v72, v76, v77
	v_cvt_pk_bf16_f32 v73, v78, v79
	v_cvt_pk_bf16_f32 v74, v80, v81
	v_cvt_pk_bf16_f32 v75, v82, v75
	flat_store_dwordx4 v[84:85], v[72:75]
	v_add_f32_e32 v68, v68, v88
	v_add_f32_e32 v69, v69, v88
	v_add_f32_e32 v70, v70, v88
	v_add_f32_e32 v71, v71, v88
	v_add_f32_e32 v64, v64, v88
	v_add_f32_e32 v65, v65, v88
	v_add_f32_e32 v66, v66, v88
	v_add_f32_e32 v67, v67, v88
	s_waitcnt vmcnt(4) lgkmcnt(0)
	s_nop 1
	v_mov_b32_e32 v72, v198
	v_mov_b32_e32 v73, v199
	v_mov_b32_e32 v74, v200
	v_mov_b32_e32 v75, v201
	v_lshlrev_b32_e32 v76, 16, v72
	v_and_b32_e32 v72, 0xffff0000, v72
	v_lshlrev_b32_e32 v77, 16, v73
	v_and_b32_e32 v73, 0xffff0000, v73
	v_lshlrev_b32_e32 v78, 16, v74
	v_and_b32_e32 v74, 0xffff0000, v74
	v_lshlrev_b32_e32 v79, 16, v75
	v_and_b32_e32 v75, 0xffff0000, v75
	v_mul_f32_e32 v68, v68, v76
	v_mul_f32_e32 v69, v69, v72
	v_mul_f32_e32 v70, v70, v77
	v_mul_f32_e32 v71, v71, v73
	v_mul_f32_e32 v64, v64, v78
	v_mul_f32_e32 v65, v65, v74
	v_mul_f32_e32 v66, v66, v79
	v_mul_f32_e32 v67, v67, v75
	v_cvt_pk_bf16_f32 v128, v68, v69
	v_cvt_pk_bf16_f32 v129, v70, v71
	v_cvt_pk_bf16_f32 v130, v64, v65
	v_cvt_pk_bf16_f32 v131, v66, v67

.LBB0_377:
	v_add_u32_e32 v64, s52, v155
	v_ashrrev_i32_e32 v65, 31, v64
	v_add_u32_e32 v74, s76, v156
	v_add_u32_e32 v66, s75, v155
	s_waitcnt lgkmcnt(0)
	v_lshl_add_u64 v[64:65], v[64:65], 2, s[4:5]
	v_mov_b64_e32 v[68:69], s[14:15]
	v_ashrrev_i32_e32 v75, 31, v74
	global_load_dword v80, v[64:65], off
	v_mad_i64_i32 v[76:77], s[48:49], v66, s62, v[68:69]
	v_lshlrev_b64 v[64:65], 1, v[74:75]
	v_lshl_add_u64 v[70:71], v[76:77], 0, v[64:65]
	flat_load_dwordx4 v[70:73], v[70:71]
	v_ashrrev_i32_e32 v67, 31, v66
	v_add_u32_e32 v144, 0x80, v74
	v_lshlrev_b64 v[66:67], 12, v[66:67]
	v_ashrrev_i32_e32 v145, 31, v144
	v_lshl_add_u64 v[74:75], s[38:39], 0, v[66:67]
	v_lshlrev_b64 v[66:67], 1, v[144:145]
	v_lshl_add_u64 v[78:79], v[74:75], 0, v[64:65]
	v_lshl_add_u64 v[76:77], v[76:77], 0, v[66:67]
	global_load_dwordx4 v[182:185], v[76:77], off
	v_add_u32_e32 v208, 16, v155
	v_add_u32_e32 v210, s75, v208
	v_mad_i64_i32 v[212:213], s[48:49], v210, s62, v[68:69]
	v_lshl_add_u64 v[206:207], v[212:213], 0, v[64:65]
	global_load_dwordx4 v[190:193], v[206:207], off
	v_add_u32_e32 v216, 16, v155
	v_add_u32_e32 v214, s52, v216
	v_ashrrev_i32_e32 v215, 31, v214
	v_lshl_add_u64 v[214:215], v[214:215], 2, s[4:5]
	global_load_dword v194, v[214:215], off
	v_add_u32_e32 v208, 16, v155
	v_add_u32_e32 v210, s75, v208
	v_mad_i64_i32 v[212:213], s[48:49], v210, s62, v[68:69]
	v_lshl_add_u64 v[206:207], v[212:213], 0, v[66:67]
	global_load_dwordx4 v[198:201], v[206:207], off
	s_waitcnt vmcnt(4)
	v_add_u32_e32 v208, 32, v155
	v_add_u32_e32 v210, s75, v208
	v_mad_i64_i32 v[212:213], s[48:49], v210, s62, v[68:69]
	v_lshl_add_u64 v[206:207], v[212:213], 0, v[64:65]
	global_load_dwordx4 v[174:177], v[206:207], off
	v_add_u32_e32 v216, 32, v155
	v_add_u32_e32 v214, s52, v216
	v_ashrrev_i32_e32 v215, 31, v214
	v_lshl_add_u64 v[214:215], v[214:215], 2, s[4:5]
	global_load_dword v178, v[214:215], off
	v_add_f32_e32 v59, v59, v80
	v_add_f32_e32 v60, v60, v80
	v_add_f32_e32 v61, v61, v80
	v_add_f32_e32 v62, v62, v80
	v_add_f32_e32 v63, v63, v80
	s_waitcnt lgkmcnt(0)
	v_lshlrev_b32_e32 v84, 16, v73
	v_and_b32_e32 v73, 0xffff0000, v73
	v_add_f32_e32 v56, v56, v80
	v_add_f32_e32 v57, v57, v80
	v_add_f32_e32 v58, v58, v80
	v_lshlrev_b32_e32 v81, 16, v70
	v_and_b32_e32 v70, 0xffff0000, v70
	v_lshlrev_b32_e32 v82, 16, v71
	v_and_b32_e32 v71, 0xffff0000, v71
	v_lshlrev_b32_e32 v83, 16, v72
	v_and_b32_e32 v72, 0xffff0000, v72
	v_mul_f32_e32 v59, v59, v73
	v_mul_f32_e32 v60, v60, v81
	v_mul_f32_e32 v61, v61, v70
	v_mul_f32_e32 v62, v62, v82
	v_mul_f32_e32 v63, v63, v71
	v_mul_f32_e32 v70, v56, v83
	v_mul_f32_e32 v71, v57, v72
	v_mul_f32_e32 v72, v58, v84
	v_cvt_pk_bf16_f32 v56, v60, v61
	v_cvt_pk_bf16_f32 v57, v62, v63
	v_cvt_pk_bf16_f32 v58, v70, v71
	v_cvt_pk_bf16_f32 v59, v72, v59
	flat_store_dwordx4 v[78:79], v[56:59]
	v_lshl_add_u64 v[72:73], v[74:75], 0, v[66:67]
	v_add_f32_e32 v52, v52, v80
	v_add_u32_e32 v61, 16, v155
	v_add_f32_e32 v53, v53, v80
	v_add_f32_e32 v48, v48, v80
	v_add_u32_e32 v60, s75, v61
	v_add_f32_e32 v51, v51, v80
	v_mad_i64_i32 v[62:63], s[48:49], v60, s62, v[68:69]
	v_add_f32_e32 v54, v54, v80
	v_add_f32_e32 v55, v55, v80
	v_add_f32_e32 v49, v49, v80
	v_add_f32_e32 v50, v50, v80
	v_lshl_add_u64 v[70:71], v[62:63], 0, v[64:65]
	s_waitcnt vmcnt(6) lgkmcnt(0)
	s_nop 1
	v_mov_b32_e32 v56, v182
	v_mov_b32_e32 v57, v183
	v_mov_b32_e32 v58, v184
	v_mov_b32_e32 v59, v185
	v_add_u32_e32 v208, 32, v155
	v_add_u32_e32 v210, s75, v208
	v_mad_i64_i32 v[212:213], s[48:49], v210, s62, v[68:69]
	v_lshl_add_u64 v[206:207], v[212:213], 0, v[66:67]
	global_load_dwordx4 v[182:185], v[206:207], off
	v_lshlrev_b32_e32 v74, 16, v56
	v_and_b32_e32 v56, 0xffff0000, v56
	v_lshlrev_b32_e32 v76, 16, v58
	v_mul_f32_e32 v52, v52, v74
	v_lshlrev_b32_e32 v77, 16, v59
	v_and_b32_e32 v59, 0xffff0000, v59
	v_mul_f32_e32 v53, v53, v56
	v_mul_f32_e32 v56, v48, v76
	v_cvt_pk_bf16_f32 v48, v52, v53
	v_add_u32_e32 v52, s52, v61
	v_lshlrev_b32_e32 v75, 16, v57
	v_and_b32_e32 v57, 0xffff0000, v57
	v_and_b32_e32 v58, 0xffff0000, v58
	v_mul_f32_e32 v51, v51, v59
	v_ashrrev_i32_e32 v53, 31, v52
	v_mul_f32_e32 v54, v54, v75
	v_mul_f32_e32 v55, v55, v57
	v_mul_f32_e32 v57, v49, v58
	v_mul_f32_e32 v58, v50, v77
	v_cvt_pk_bf16_f32 v49, v54, v55
	v_cvt_pk_bf16_f32 v50, v56, v57
	v_cvt_pk_bf16_f32 v51, v58, v51
	flat_store_dwordx4 v[72:73], v[48:51]
	v_lshl_add_u64 v[52:53], v[52:53], 2, s[4:5]
	v_ashrrev_i32_e32 v61, 31, v60
	v_lshlrev_b64 v[52:53], 12, v[60:61]
	v_lshl_add_u64 v[52:53], s[38:39], 0, v[52:53]
	v_lshl_add_u64 v[54:55], v[62:63], 0, v[66:67]
	v_lshl_add_u64 v[56:57], v[52:53], 0, v[64:65]
	s_waitcnt vmcnt(6) lgkmcnt(0)
	s_nop 1
	v_mov_b32_e32 v48, v190
	v_mov_b32_e32 v49, v191
	v_mov_b32_e32 v50, v192
	v_mov_b32_e32 v51, v193
	v_mov_b32_e32 v58, v194
	v_add_u32_e32 v208, 48, v155
	v_add_u32_e32 v210, s75, v208
	v_mad_i64_i32 v[212:213], s[48:49], v210, s62, v[68:69]
	v_lshl_add_u64 v[206:207], v[212:213], 0, v[64:65]
	global_load_dwordx4 v[190:193], v[206:207], off
	v_add_u32_e32 v216, 48, v155
	v_add_u32_e32 v214, s52, v216
	v_ashrrev_i32_e32 v215, 31, v214
	v_lshl_add_u64 v[214:215], v[214:215], 2, s[4:5]
	global_load_dword v194, v[214:215], off
	v_lshlrev_b32_e32 v62, 16, v51
	v_and_b32_e32 v51, 0xffff0000, v51
	v_add_f32_e32 v43, v43, v58
	v_lshlrev_b32_e32 v59, 16, v48
	v_and_b32_e32 v48, 0xffff0000, v48
	v_lshlrev_b32_e32 v60, 16, v49
	v_and_b32_e32 v49, 0xffff0000, v49
	v_lshlrev_b32_e32 v61, 16, v50
	v_and_b32_e32 v50, 0xffff0000, v50
	v_add_f32_e32 v44, v44, v58
	v_add_f32_e32 v45, v45, v58
	v_add_f32_e32 v46, v46, v58
	v_add_f32_e32 v47, v47, v58
	v_add_f32_e32 v40, v40, v58
	v_add_f32_e32 v41, v41, v58
	v_add_f32_e32 v42, v42, v58
	v_mul_f32_e32 v43, v43, v51
	v_mul_f32_e32 v44, v44, v59
	v_mul_f32_e32 v45, v45, v48
	v_mul_f32_e32 v46, v46, v60
	v_mul_f32_e32 v47, v47, v49
	v_mul_f32_e32 v48, v40, v61
	v_mul_f32_e32 v49, v41, v50
	v_mul_f32_e32 v50, v42, v62
	v_cvt_pk_bf16_f32 v40, v44, v45
	v_cvt_pk_bf16_f32 v41, v46, v47
	v_cvt_pk_bf16_f32 v42, v48, v49
	v_cvt_pk_bf16_f32 v43, v50, v43
	flat_store_dwordx4 v[56:57], v[40:43]
	v_lshl_add_u64 v[50:51], v[52:53], 0, v[66:67]
	v_add_f32_e32 v36, v36, v58
	v_add_u32_e32 v45, 32, v155
	v_add_f32_e32 v37, v37, v58
	v_add_f32_e32 v32, v32, v58
	v_add_u32_e32 v44, s75, v45
	v_add_f32_e32 v35, v35, v58
	v_mad_i64_i32 v[46:47], s[48:49], v44, s62, v[68:69]
	v_add_f32_e32 v38, v38, v58
	v_add_f32_e32 v39, v39, v58
	v_add_f32_e32 v33, v33, v58
	v_add_f32_e32 v34, v34, v58
	v_lshl_add_u64 v[48:49], v[46:47], 0, v[64:65]
	s_waitcnt vmcnt(8) lgkmcnt(0)
	s_nop 1
	v_mov_b32_e32 v40, v198
	v_mov_b32_e32 v41, v199
	v_mov_b32_e32 v42, v200
	v_mov_b32_e32 v43, v201
	v_add_u32_e32 v208, 48, v155
	v_add_u32_e32 v210, s75, v208
	v_mad_i64_i32 v[212:213], s[48:49], v210, s62, v[68:69]
	v_lshl_add_u64 v[206:207], v[212:213], 0, v[66:67]
	global_load_dwordx4 v[198:201], v[206:207], off
	v_lshlrev_b32_e32 v52, 16, v40
	v_and_b32_e32 v40, 0xffff0000, v40
	v_lshlrev_b32_e32 v54, 16, v42
	v_mul_f32_e32 v36, v36, v52
	v_lshlrev_b32_e32 v55, 16, v43
	v_and_b32_e32 v43, 0xffff0000, v43
	v_mul_f32_e32 v37, v37, v40
	v_mul_f32_e32 v40, v32, v54
	v_cvt_pk_bf16_f32 v32, v36, v37
	v_add_u32_e32 v36, s52, v45
	v_lshlrev_b32_e32 v53, 16, v41
	v_and_b32_e32 v41, 0xffff0000, v41
	v_and_b32_e32 v42, 0xffff0000, v42
	v_mul_f32_e32 v35, v35, v43
	v_ashrrev_i32_e32 v37, 31, v36
	v_mul_f32_e32 v38, v38, v53
	v_mul_f32_e32 v39, v39, v41
	v_mul_f32_e32 v41, v33, v42
	v_mul_f32_e32 v42, v34, v55
	v_cvt_pk_bf16_f32 v33, v38, v39
	v_cvt_pk_bf16_f32 v34, v40, v41
	v_cvt_pk_bf16_f32 v35, v42, v35
	flat_store_dwordx4 v[50:51], v[32:35]
	v_lshl_add_u64 v[36:37], v[36:37], 2, s[4:5]
	v_ashrrev_i32_e32 v45, 31, v44
	v_lshlrev_b64 v[36:37], 12, v[44:45]
	v_lshl_add_u64 v[36:37], s[38:39], 0, v[36:37]
	v_lshl_add_u64 v[38:39], v[46:47], 0, v[66:67]
	v_lshl_add_u64 v[40:41], v[36:37], 0, v[64:65]
	s_waitcnt vmcnt(8) lgkmcnt(0)
	s_nop 1
	v_mov_b32_e32 v32, v174
	v_mov_b32_e32 v33, v175
	v_mov_b32_e32 v34, v176
	v_mov_b32_e32 v35, v177
	v_mov_b32_e32 v42, v178
	v_lshlrev_b32_e32 v46, 16, v35
	v_and_b32_e32 v35, 0xffff0000, v35
	v_add_f32_e32 v27, v27, v42
	v_lshlrev_b32_e32 v43, 16, v32
	v_and_b32_e32 v32, 0xffff0000, v32
	v_lshlrev_b32_e32 v44, 16, v33
	v_and_b32_e32 v33, 0xffff0000, v33
	v_lshlrev_b32_e32 v45, 16, v34
	v_and_b32_e32 v34, 0xffff0000, v34
	v_add_f32_e32 v28, v28, v42
	v_add_f32_e32 v29, v29, v42
	v_add_f32_e32 v30, v30, v42
	v_add_f32_e32 v31, v31, v42
	v_add_f32_e32 v24, v24, v42
	v_add_f32_e32 v25, v25, v42
	v_add_f32_e32 v26, v26, v42
	v_mul_f32_e32 v27, v27, v35
	v_mul_f32_e32 v28, v28, v43
	v_mul_f32_e32 v29, v29, v32
	v_mul_f32_e32 v30, v30, v44
	v_mul_f32_e32 v31, v31, v33
	v_mul_f32_e32 v32, v24, v45
	v_mul_f32_e32 v33, v25, v34
	v_mul_f32_e32 v34, v26, v46
	v_cvt_pk_bf16_f32 v24, v28, v29
	v_cvt_pk_bf16_f32 v25, v30, v31
	v_cvt_pk_bf16_f32 v26, v32, v33
	v_cvt_pk_bf16_f32 v27, v34, v27
	flat_store_dwordx4 v[40:41], v[24:27]
	v_lshl_add_u64 v[34:35], v[36:37], 0, v[66:67]
	v_add_f32_e32 v20, v20, v42
	v_add_u32_e32 v29, 48, v155
	v_add_f32_e32 v21, v21, v42
	v_add_f32_e32 v16, v16, v42
	v_add_u32_e32 v28, s75, v29
	v_add_f32_e32 v19, v19, v42
	v_mad_i64_i32 v[30:31], s[48:49], v28, s62, v[68:69]
	v_add_f32_e32 v22, v22, v42
	v_add_f32_e32 v23, v23, v42
	v_add_f32_e32 v17, v17, v42
	v_add_f32_e32 v18, v18, v42
	v_lshl_add_u64 v[32:33], v[30:31], 0, v[64:65]
	s_waitcnt vmcnt(7) lgkmcnt(0)
	s_nop 1
	v_mov_b32_e32 v24, v182
	v_mov_b32_e32 v25, v183
	v_mov_b32_e32 v26, v184
	v_mov_b32_e32 v27, v185
	v_lshlrev_b32_e32 v36, 16, v24
	v_and_b32_e32 v24, 0xffff0000, v24
	v_lshlrev_b32_e32 v38, 16, v26
	v_mul_f32_e32 v20, v20, v36
	v_lshlrev_b32_e32 v39, 16, v27
	v_and_b32_e32 v27, 0xffff0000, v27
	v_mul_f32_e32 v21, v21, v24
	v_mul_f32_e32 v24, v16, v38
	v_cvt_pk_bf16_f32 v16, v20, v21
	v_add_u32_e32 v20, s52, v29
	v_lshlrev_b32_e32 v37, 16, v25
	v_and_b32_e32 v25, 0xffff0000, v25
	v_and_b32_e32 v26, 0xffff0000, v26
	v_mul_f32_e32 v19, v19, v27
	v_ashrrev_i32_e32 v21, 31, v20
	v_mul_f32_e32 v22, v22, v37
	v_mul_f32_e32 v23, v23, v25
	v_mul_f32_e32 v25, v17, v26
	v_mul_f32_e32 v26, v18, v39
	v_cvt_pk_bf16_f32 v17, v22, v23
	v_cvt_pk_bf16_f32 v18, v24, v25
	v_cvt_pk_bf16_f32 v19, v26, v19
	flat_store_dwordx4 v[34:35], v[16:19]
	v_lshl_add_u64 v[20:21], v[20:21], 2, s[4:5]
	v_ashrrev_i32_e32 v29, 31, v28
	v_lshlrev_b64 v[146:147], 12, v[28:29]
	v_lshl_add_u64 v[20:21], s[38:39], 0, v[146:147]
	v_lshl_add_u64 v[20:21], v[20:21], 0, v[64:65]
	v_lshl_add_u64 v[22:23], v[30:31], 0, v[66:67]
	s_waitcnt vmcnt(5) lgkmcnt(0)
	s_nop 1
	v_mov_b32_e32 v16, v190
	v_mov_b32_e32 v17, v191
	v_mov_b32_e32 v18, v192
	v_mov_b32_e32 v19, v193
	v_mov_b32_e32 v24, v194
	v_lshlrev_b32_e32 v28, 16, v19
	v_and_b32_e32 v19, 0xffff0000, v19
	v_add_f32_e32 v11, v11, v24
	v_lshlrev_b32_e32 v25, 16, v16
	v_and_b32_e32 v16, 0xffff0000, v16
	v_lshlrev_b32_e32 v26, 16, v17
	v_and_b32_e32 v17, 0xffff0000, v17
	v_lshlrev_b32_e32 v27, 16, v18
	v_and_b32_e32 v18, 0xffff0000, v18
	v_add_f32_e32 v12, v12, v24
	v_add_f32_e32 v13, v13, v24
	v_add_f32_e32 v14, v14, v24
	v_add_f32_e32 v15, v15, v24
	v_add_f32_e32 v8, v8, v24
	v_add_f32_e32 v9, v9, v24
	v_add_f32_e32 v10, v10, v24
	v_mul_f32_e32 v11, v11, v19
	v_mul_f32_e32 v12, v12, v25
	v_mul_f32_e32 v13, v13, v16
	v_mul_f32_e32 v14, v14, v26
	v_mul_f32_e32 v15, v15, v17
	v_mul_f32_e32 v16, v8, v27
	v_mul_f32_e32 v17, v9, v18
	v_mul_f32_e32 v18, v10, v28
	v_cvt_pk_bf16_f32 v8, v12, v13
	v_cvt_pk_bf16_f32 v9, v14, v15
	v_cvt_pk_bf16_f32 v10, v16, v17
	v_cvt_pk_bf16_f32 v11, v18, v11
	flat_store_dwordx4 v[20:21], v[8:11]
	v_add_f32_e32 v4, v4, v24
	v_add_f32_e32 v5, v5, v24
	v_add_f32_e32 v6, v6, v24
	v_add_f32_e32 v7, v7, v24
	v_add_f32_e32 v0, v0, v24
	v_add_f32_e32 v1, v1, v24
	v_add_f32_e32 v2, v2, v24
	v_add_f32_e32 v3, v3, v24
	s_waitcnt vmcnt(4) lgkmcnt(0)
	s_nop 1
	v_mov_b32_e32 v8, v198
	v_mov_b32_e32 v9, v199
	v_mov_b32_e32 v10, v200
	v_mov_b32_e32 v11, v201
	v_lshlrev_b32_e32 v12, 16, v8
	v_and_b32_e32 v8, 0xffff0000, v8
	v_lshlrev_b32_e32 v13, 16, v9
	v_and_b32_e32 v9, 0xffff0000, v9
	v_lshlrev_b32_e32 v14, 16, v10
	v_and_b32_e32 v10, 0xffff0000, v10
	v_lshlrev_b32_e32 v15, 16, v11
	v_and_b32_e32 v11, 0xffff0000, v11
	v_mul_f32_e32 v4, v4, v12
	v_mul_f32_e32 v5, v5, v8
	v_mul_f32_e32 v6, v6, v13
	v_mul_f32_e32 v7, v7, v9
	v_mul_f32_e32 v0, v0, v14
	v_mul_f32_e32 v1, v1, v10
	v_mul_f32_e32 v2, v2, v15
	v_mul_f32_e32 v3, v3, v11
	v_cvt_pk_bf16_f32 v128, v4, v5
	v_cvt_pk_bf16_f32 v129, v6, v7
	v_cvt_pk_bf16_f32 v130, v0, v1
	v_cvt_pk_bf16_f32 v131, v2, v3
	s_cbranch_execnz .LBB0_372
	s_branch .LBB0_373
